# v75 + attention second-half MFMA hoist (s_nop 5 -> 0) + first QK^T MFMA of each half-step issued ahead of its lead-in instructions (stack of the individually neutral-to-positive edits)
# baseline (speedup 1.0000x reference)
.LBB0_1607:
	s_add_i32 s22, s28, 0x2000
	s_cmpk_lg_i32 s28, 0x4000
	s_cselect_b32 s61, s22, 0
	v_add_f32_e32 v15, v116, v14
	v_mfma_f32_32x32x16_bf16 v[112:127], v[112:115], v[172:175], 0
	v_add_u32_e32 v14, s29, v244
	ds_read_b64_tr_b16 v[196:197], v14 offset:24576
	ds_read_b64_tr_b16 v[198:199], v14 offset:25088
	v_add_f32_e32 v132, v87, v88
	v_cvt_pk_bf16_f32 v156, v96, v97
	v_cvt_pk_bf16_f32 v157, v98, v99
	ds_read_b64_tr_b16 v[192:193], v14 offset:28672
	ds_read_b64_tr_b16 v[194:195], v14 offset:29184
	v_add_f32_e32 v96, v89, v132
	v_cvt_pk_bf16_f32 v158, v100, v101
	v_cvt_pk_bf16_f32 v159, v102, v103
	v_mfma_f32_32x32x16_bf16 v[128:143], v[128:131], v[172:175], 0
	ds_read_b64_tr_b16 v[188:189], v14 offset:25600
	ds_read_b64_tr_b16 v[190:191], v14 offset:26112
	v_add_f32_e32 v96, v90, v96
	v_cvt_pk_bf16_f32 v152, v104, v105
	v_cvt_pk_bf16_f32 v153, v106, v107
	v_mfma_f32_32x32x16_bf16 v[112:127], v[184:187], v[168:171], v[112:127]
	ds_read_b64_tr_b16 v[184:185], v14 offset:29696
	ds_read_b64_tr_b16 v[186:187], v14 offset:30208
	v_add_f32_e32 v96, v91, v96
	v_cvt_pk_bf16_f32 v154, v108, v109
	v_cvt_pk_bf16_f32 v155, v110, v111
	v_mfma_f32_32x32x16_bf16 v[128:143], v[176:179], v[168:171], v[128:143]
	ds_read_b64_tr_b16 v[176:177], v14 offset:26624
	ds_read_b64_tr_b16 v[178:179], v14 offset:27136
	v_add_f32_e32 v96, v92, v96
	v_cvt_pk_bf16_f32 v148, v80, v81
	v_cvt_pk_bf16_f32 v149, v82, v83
	v_mfma_f32_32x32x16_bf16 v[112:127], v[180:183], v[164:167], v[112:127]
	v_mfma_f32_32x32x16_bf16 v[128:143], v[6:9], v[164:167], v[128:143]
	ds_read_b64_tr_b16 v[212:213], v14 offset:30720
	ds_read_b64_tr_b16 v[214:215], v14 offset:31232
	v_add_f32_e32 v80, v93, v96
	v_cvt_pk_bf16_f32 v150, v84, v85
	v_cvt_pk_bf16_f32 v151, v86, v87
	v_mfma_f32_32x32x16_bf16 v[112:127], v[10:13], v[160:163], v[112:127]
	ds_read_b64_tr_b16 v[208:209], v14 offset:27648
	ds_read_b64_tr_b16 v[210:211], v14 offset:28160
	v_add_f32_e32 v80, v94, v80
	v_cvt_pk_bf16_f32 v144, v88, v89
	v_cvt_pk_bf16_f32 v145, v90, v91
	ds_read_b64_tr_b16 v[6:7], v14 offset:31744
	ds_read_b64_tr_b16 v[8:9], v14 offset:32256
	v_add_f32_e32 v10, v95, v80
	v_cvt_pk_bf16_f32 v146, v92, v93
	v_cvt_pk_bf16_f32 v147, v94, v95
	v_mfma_f32_32x32x16_bf16 v[128:143], v[2:5], v[160:163], v[128:143]
	s_nop 0
	v_add_f32_e64 v4, v112, -v228
	v_add_f32_e64 v5, v113, -v228
	v_pk_add_f32 v[98:99], v[114:115], v[228:229] op_sel_hi:[1,0] neg_lo:[0,1] neg_hi:[0,1]
	v_pk_add_f32 v[100:101], v[116:117], v[228:229] op_sel_hi:[1,0] neg_lo:[0,1] neg_hi:[0,1]
	v_pk_add_f32 v[102:103], v[118:119], v[228:229] op_sel_hi:[1,0] neg_lo:[0,1] neg_hi:[0,1]
	v_pk_add_f32 v[104:105], v[120:121], v[228:229] op_sel_hi:[1,0] neg_lo:[0,1] neg_hi:[0,1]
	v_pk_add_f32 v[106:107], v[122:123], v[228:229] op_sel_hi:[1,0] neg_lo:[0,1] neg_hi:[0,1]
	v_pk_add_f32 v[108:109], v[124:125], v[228:229] op_sel_hi:[1,0] neg_lo:[0,1] neg_hi:[0,1]
	v_pk_add_f32 v[110:111], v[126:127], v[228:229] op_sel_hi:[1,0] neg_lo:[0,1] neg_hi:[0,1]
	v_max_f32_e32 v11, v4, v5
	s_add_u32 s22, s30, 0xa0000
	v_pk_add_f32 v[2:3], v[128:129], v[228:229] op_sel_hi:[1,0] neg_lo:[0,1] neg_hi:[0,1]
	v_max3_f32 v12, v98, v99, v100
	v_pk_add_f32 v[82:83], v[130:131], v[228:229] op_sel_hi:[1,0] neg_lo:[0,1] neg_hi:[0,1]
	v_max3_f32 v11, v11, v101, v102
	v_pk_add_f32 v[84:85], v[132:133], v[228:229] op_sel_hi:[1,0] neg_lo:[0,1] neg_hi:[0,1]
	v_max3_f32 v12, v12, v103, v104
	v_pk_add_f32 v[86:87], v[134:135], v[228:229] op_sel_hi:[1,0] neg_lo:[0,1] neg_hi:[0,1]
	v_max3_f32 v11, v11, v105, v106
	v_pk_add_f32 v[88:89], v[136:137], v[228:229] op_sel_hi:[1,0] neg_lo:[0,1] neg_hi:[0,1]
	v_max3_f32 v12, v12, v107, v108
	v_pk_add_f32 v[90:91], v[138:139], v[228:229] op_sel_hi:[1,0] neg_lo:[0,1] neg_hi:[0,1]
	v_max3_f32 v11, v11, v109, v110
	v_pk_add_f32 v[92:93], v[140:141], v[228:229] op_sel_hi:[1,0] neg_lo:[0,1] neg_hi:[0,1]
	v_max3_f32 v12, v12, v111, v2
	v_pk_add_f32 v[94:95], v[142:143], v[228:229] op_sel_hi:[1,0] neg_lo:[0,1] neg_hi:[0,1]
	v_max3_f32 v11, v11, v3, v82
	v_max3_f32 v12, v12, v83, v84
	v_max3_f32 v11, v11, v85, v86
	v_max3_f32 v12, v12, v87, v88
	v_max3_f32 v11, v11, v89, v90
	v_max3_f32 v12, v12, v91, v92
	v_max3_f32 v11, v11, v94, v95
	v_max3_f32 v11, v11, v93, v12
	s_addc_u32 s23, s31, 0
	s_add_i32 s24, s28, s57
	v_mov_b32_e32 v12, v11
	s_mov_b32 s25, m0
	s_mov_b32 m0, s24
	s_nop 0
	global_load_lds_dwordx4 v241, s[22:23]
	s_mov_b32 m0, s25
	s_add_u32 s22, s62, 0x60000
	s_nop 0
	v_permlane32_swap_b32_e32 v11, v12
	s_addc_u32 s23, s63, 0
	s_add_i32 s24, s61, s58
	s_mov_b32 s25, m0
	s_mov_b32 m0, s24
	s_nop 0
	global_load_lds_dwordx4 v242, s[22:23]
	s_mov_b32 m0, s25
	s_add_u32 s22, s64, 0x60000
	v_max_f32_e32 v11, v11, v12
	s_addc_u32 s23, s65, 0
	s_add_i32 s24, s61, s59
	s_mov_b32 s25, m0
	s_mov_b32 m0, s24
	s_nop 0
	global_load_lds_dwordx4 v242, s[22:23]
	s_mov_b32 m0, s25
	v_cmp_lt_f32_e32 vcc, s35, v11
	s_cmp_lg_u64 vcc, 0
	v_add_f32_e32 v10, v15, v10
	s_cselect_b64 s[22:23], -1, 0
	s_cbranch_vccnz .LBB0_1615
